# P5 epilogue: dropped the L1 invalidate after the panel flag wait (xbuf is read with sc1 loads that bypass L1); on top of P1 prologue/ring and P5 load pipelining
# speedup vs baseline: 1.0055x; 1.0055x over previous
;     __device__ __forceinline__ void operator()(f32x4 (&acc)[2][2][4][2], const Unit& u, int wr, int wc, int fr, int fq, LAS unsigned char* lds) const {
;     ...
;         if (t_ == 0) { unsigned* f = flags + u.pm * 16;
;             (void)__hip_atomic_fetch_add(f, 1u, __ATOMIC_RELAXED, __HIP_MEMORY_SCOPE_AGENT);
;             unsigned sp = 0u;
;             while (__hip_atomic_load(f, __ATOMIC_RELAXED, __HIP_MEMORY_SCOPE_AGENT) < 4u) { __builtin_amdgcn_s_sleep(1); if (++sp > (1u << 22)) break; }
;             __builtin_amdgcn_fence(__ATOMIC_ACQUIRE, "agent");
;             asm volatile("s_waitcnt vmcnt(0)" ::: "memory"); }
;         __syncthreads();
;         if (t_ < 256) { float tot = 0.f;
; #pragma unroll
;             for (int q = 0; q < 4; ++q) tot += __hip_atomic_load(xbuf + (size_t)(u.pm * 4 + q) * 256 + t_, __ATOMIC_RELAXED, __HIP_MEMORY_SCOPE_AGENT);
;             S[t_] = rsqrtf(tot * (1.f / DM) + EPS); }
.LBB0_1240:
	global_load_dword v0, v153, s[44:45] sc1
	s_mov_b64 s[46:47], -1
	s_waitcnt vmcnt(0)
	v_cmp_lt_u32_e32 vcc, 3, v0
	s_cbranch_vccnz .LBB0_1239
	s_sleep 1
	global_load_dword v0, v153, s[44:45] sc1
	s_waitcnt vmcnt(0)
	v_cmp_gt_u32_e32 vcc, 4, v0
	s_cbranch_vccz .LBB0_1239
	s_sleep 1
	global_load_dword v0, v153, s[44:45] sc1
	s_waitcnt vmcnt(0)
	v_cmp_gt_u32_e32 vcc, 4, v0
	s_cbranch_vccz .LBB0_1239
	s_sleep 1
	global_load_dword v0, v153, s[44:45] sc1
	s_waitcnt vmcnt(0)
	v_cmp_gt_u32_e32 vcc, 4, v0
	s_cbranch_vccz .LBB0_1239
	s_sleep 1
	global_load_dword v0, v153, s[44:45] sc1
	s_waitcnt vmcnt(0)
	v_cmp_gt_u32_e32 vcc, 4, v0
	s_cbranch_vccz .LBB0_1239
	s_add_i32 s16, s16, -5
	s_cmp_eq_u32 s16, 0
	s_cselect_b64 s[46:47], -1, 0
	s_sleep 1
	s_branch .LBB0_1239
.LBB0_1246:
	s_waitcnt vmcnt(0)
.LBB0_1247:
	s_or_b64 exec, exec, s[42:43]
	s_barrier
	s_and_saveexec_b64 s[42:43], s[4:5]
	s_cbranch_execz .LBB0_1249
	s_lshl_b32 s4, s73, 2
	s_ashr_i32 s5, s4, 31
	v_lshl_add_u64 v[0:1], v[160:161], 2, s[10:11]
	s_lshl_b64 s[16:17], s[4:5], 10
	v_lshl_add_u64 v[2:3], v[0:1], 0, s[16:17]
	s_or_b32 s16, s4, 1
	s_ashr_i32 s17, s16, 31
	s_lshl_b64 s[16:17], s[16:17], 10
	global_load_dword v4, v[2:3], off sc1
	v_lshl_add_u64 v[2:3], v[0:1], 0, s[16:17]
	s_or_b32 s16, s4, 2
	s_ashr_i32 s17, s16, 31
	s_or_b32 s4, s4, 3
	s_lshl_b64 s[16:17], s[16:17], 10
	s_ashr_i32 s5, s4, 31
	global_load_dword v5, v[2:3], off sc1
	v_lshl_add_u64 v[2:3], v[0:1], 0, s[16:17]
	s_lshl_b64 s[4:5], s[4:5], 10
	global_load_dword v2, v[2:3], off sc1
	v_lshl_add_u64 v[0:1], v[0:1], 0, s[4:5]
	global_load_dword v0, v[0:1], off sc1
	s_waitcnt vmcnt(3)
	v_add_f32_e32 v1, 0, v4
	s_waitcnt vmcnt(2)
	v_add_f32_e32 v1, v1, v5
	s_waitcnt vmcnt(1)
	v_add_f32_e32 v1, v1, v2
	s_waitcnt vmcnt(0)
	v_add_f32_e32 v0, v1, v0
	v_fmamk_f32 v0, v0, 0x3a800000, v181
	v_mul_f32_e32 v1, 0x4b800000, v0
	v_cmp_gt_f32_e32 vcc, s69, v0
	s_nop 1
	v_cndmask_b32_e32 v0, v0, v1, vcc
	v_rsq_f32_e32 v0, v0
	v_lshl_add_u32 v1, v160, 2, 0
	v_add_u32_e32 v1, 0x22000, v1
	v_mul_f32_e32 v2, 0x45800000, v0
	v_cndmask_b32_e32 v0, v0, v2, vcc
	ds_write_b32 v1, v0
